# v18 = v13 with every wave taking the per-step barrier between QK^T and PV (no predicate; no end-of-step barrier)
# speedup vs baseline: 1.0021x; 1.0021x over previous
.LBB0_577:
	s_waitcnt vmcnt(3) lgkmcnt(0)
	s_barrier
	ds_read_b64_tr_b16 v[40:41], v167 offset:54272
	ds_read_b64_tr_b16 v[42:43], v167 offset:54784
	s_waitcnt lgkmcnt(6)
	v_mfma_f32_32x32x16_bf16 v[16:31], v[132:135], v[32:35], v[16:31]
	v_exp_f32_e32 v80, v80
	v_exp_f32_e32 v81, v81
	v_exp_f32_e32 v82, v82
	v_exp_f32_e32 v83, v83
	ds_read_b64_tr_b16 v[32:33], v167 offset:51200
	ds_read_b64_tr_b16 v[34:35], v167 offset:51712
	s_waitcnt lgkmcnt(6)
	v_mfma_f32_32x32x16_bf16 v[0:15], v[132:135], v[48:51], v[0:15]
	v_exp_f32_e32 v84, v84
	v_exp_f32_e32 v85, v85
	v_exp_f32_e32 v86, v86
	v_exp_f32_e32 v87, v87
	ds_read_b64_tr_b16 v[44:45], v167 offset:55296
	ds_read_b64_tr_b16 v[46:47], v167 offset:55808
	s_waitcnt lgkmcnt(6)
	v_mfma_f32_32x32x16_bf16 v[16:31], v[128:131], v[36:39], v[16:31]
	v_exp_f32_e32 v88, v88
	v_exp_f32_e32 v89, v89
	v_exp_f32_e32 v90, v90
	v_exp_f32_e32 v91, v91
	ds_read_b64_tr_b16 v[48:49], v167 offset:52224
	ds_read_b64_tr_b16 v[50:51], v167 offset:52736
	s_waitcnt lgkmcnt(6)
	v_mfma_f32_32x32x16_bf16 v[0:15], v[128:131], v[40:43], v[0:15]
	v_exp_f32_e32 v92, v92
	v_exp_f32_e32 v93, v93
	v_exp_f32_e32 v94, v94
	v_exp_f32_e32 v95, v95
	ds_read_b64_tr_b16 v[40:41], v167 offset:56320
	ds_read_b64_tr_b16 v[42:43], v167 offset:56832
	s_waitcnt lgkmcnt(6)
	v_mfma_f32_32x32x16_bf16 v[16:31], v[124:127], v[32:35], v[16:31]
	v_exp_f32_e32 v64, v64
	v_exp_f32_e32 v65, v65
	v_exp_f32_e32 v66, v66
	v_exp_f32_e32 v67, v67
	v_add_u32_e32 v142, s83, v179
	ds_read_b128 v[32:35], v142
	s_waitcnt lgkmcnt(5)
	v_mfma_f32_32x32x16_bf16 v[0:15], v[124:127], v[44:47], v[0:15]
	v_exp_f32_e32 v68, v68
	v_exp_f32_e32 v69, v69
	v_exp_f32_e32 v70, v70
	v_exp_f32_e32 v71, v71
	ds_read_b128 v[36:39], v142 offset:512
	s_waitcnt lgkmcnt(4)
	v_mfma_f32_32x32x16_bf16 v[16:31], v[120:123], v[48:51], v[16:31]
	v_exp_f32_e32 v72, v72
	v_exp_f32_e32 v73, v73
	v_exp_f32_e32 v74, v74
	v_exp_f32_e32 v75, v75
	ds_read_b128 v[136:139], v142 offset:2048
	s_waitcnt lgkmcnt(3)
	v_mfma_f32_32x32x16_bf16 v[0:15], v[120:123], v[40:43], v[0:15]
	v_exp_f32_e32 v76, v76
	v_exp_f32_e32 v77, v77
	v_exp_f32_e32 v78, v78
	v_exp_f32_e32 v79, v79
	s_andn2_b64 vcc, exec, s[60:61]
	s_cbranch_vccnz .LBB0_579
	s_waitcnt lgkmcnt(0)
	v_add_u32_e32 v52, s54, v146
	ds_read_b128 v[40:43], v52 offset:96
	ds_read_b128 v[44:47], v52 offset:64
	ds_read_b128 v[48:51], v52 offset:32
	ds_read_b128 v[52:55], v52
	s_waitcnt lgkmcnt(3)
	v_pk_mul_f32 v[28:29], v[28:29], v[40:41]
	s_waitcnt lgkmcnt(2)
	v_pk_mul_f32 v[24:25], v[24:25], v[44:45]
	s_waitcnt lgkmcnt(1)
	v_pk_mul_f32 v[20:21], v[20:21], v[48:49]
	v_pk_mul_f32 v[30:31], v[30:31], v[42:43]
	v_pk_mul_f32 v[26:27], v[26:27], v[46:47]
	v_pk_mul_f32 v[22:23], v[22:23], v[50:51]
	s_waitcnt lgkmcnt(0)
	v_pk_mul_f32 v[18:19], v[18:19], v[54:55]
	v_pk_mul_f32 v[16:17], v[16:17], v[52:53]
	v_pk_mul_f32 v[12:13], v[12:13], v[40:41]
	v_pk_mul_f32 v[8:9], v[8:9], v[44:45]
	v_pk_mul_f32 v[4:5], v[4:5], v[48:49]
	v_pk_mul_f32 v[14:15], v[14:15], v[42:43]
	v_pk_mul_f32 v[10:11], v[10:11], v[46:47]
	v_pk_mul_f32 v[6:7], v[6:7], v[50:51]
	v_pk_mul_f32 v[2:3], v[2:3], v[54:55]
	v_pk_mul_f32 v[0:1], v[0:1], v[52:53]

.LBB0_585:
	s_waitcnt vmcnt(3) lgkmcnt(0)
	s_barrier
	s_add_i32 s0, s83, 0x3000
	s_cmpk_lg_u32 s83, 0x9000
	s_cselect_b32 s82, s0, 0
	ds_read_b64_tr_b16 v[72:73], v141 offset:54272
	ds_read_b64_tr_b16 v[74:75], v141 offset:54784
	s_waitcnt lgkmcnt(6)
	v_mfma_f32_32x32x16_bf16 v[16:31], v[132:135], v[64:67], v[16:31]
	v_exp_f32_e32 v48, v48
	v_exp_f32_e32 v49, v49
	v_exp_f32_e32 v50, v50
	v_exp_f32_e32 v51, v51
	ds_read_b64_tr_b16 v[64:65], v141 offset:51200
	ds_read_b64_tr_b16 v[66:67], v141 offset:51712
	s_waitcnt lgkmcnt(6)
	v_mfma_f32_32x32x16_bf16 v[0:15], v[132:135], v[80:83], v[0:15]
	v_exp_f32_e32 v52, v52
	v_exp_f32_e32 v53, v53
	v_exp_f32_e32 v54, v54
	v_exp_f32_e32 v55, v55
	s_add_i32 s0, s79, 0x2000
	s_cmpk_lg_i32 s79, 0x4000
	s_cselect_b32 s0, s0, 0xe800
	s_cmpk_lg_u32 s79, 0xe800
	s_cselect_b32 s84, s0, 0
	ds_read_b64_tr_b16 v[76:77], v141 offset:55296
	ds_read_b64_tr_b16 v[78:79], v141 offset:55808
	s_waitcnt lgkmcnt(6)
	v_mfma_f32_32x32x16_bf16 v[16:31], v[128:131], v[68:71], v[16:31]
	v_exp_f32_e32 v56, v56
	v_exp_f32_e32 v57, v57
	v_exp_f32_e32 v58, v58
	v_exp_f32_e32 v59, v59
	s_add_i32 s0, s82, 0x3000
	s_cmpk_lg_u32 s82, 0x9000
	s_cselect_b32 s85, s0, 0
	ds_read_b64_tr_b16 v[68:69], v141 offset:52224
	ds_read_b64_tr_b16 v[70:71], v141 offset:52736
	s_waitcnt lgkmcnt(6)
	v_mfma_f32_32x32x16_bf16 v[0:15], v[128:131], v[72:75], v[0:15]
	v_exp_f32_e32 v60, v60
	v_exp_f32_e32 v61, v61
	v_exp_f32_e32 v62, v62
	v_exp_f32_e32 v63, v63
	s_add_u32 s68, s68, 0x30000
	s_addc_u32 s69, s69, 0
	ds_read_b64_tr_b16 v[72:73], v141 offset:56320
	ds_read_b64_tr_b16 v[74:75], v141 offset:56832
	s_waitcnt lgkmcnt(6)
	v_mfma_f32_32x32x16_bf16 v[16:31], v[124:127], v[64:67], v[16:31]
	v_exp_f32_e32 v32, v32
	v_exp_f32_e32 v33, v33
	v_exp_f32_e32 v34, v34
	v_exp_f32_e32 v35, v35
	s_add_u32 s48, s48, 0x48000
	s_addc_u32 s49, s49, 0
	v_add_u32_e32 v64, s82, v179
	ds_read_b128 v[80:83], v64
	s_waitcnt lgkmcnt(5)
	v_mfma_f32_32x32x16_bf16 v[0:15], v[124:127], v[76:79], v[0:15]
	v_exp_f32_e32 v36, v36
	v_exp_f32_e32 v37, v37
	v_exp_f32_e32 v38, v38
	v_exp_f32_e32 v39, v39
	s_add_u32 s8, s8, 0x2000
	s_addc_u32 s9, s9, 0
	ds_read_b128 v[136:139], v64 offset:512
	s_waitcnt lgkmcnt(4)
	v_mfma_f32_32x32x16_bf16 v[16:31], v[120:123], v[68:71], v[16:31]
	v_exp_f32_e32 v40, v40
	v_exp_f32_e32 v41, v41
	v_exp_f32_e32 v42, v42
	v_exp_f32_e32 v43, v43
	s_add_i32 s0, s87, 2
	ds_read_b128 v[140:143], v64 offset:2048
	s_waitcnt lgkmcnt(3)
	v_mfma_f32_32x32x16_bf16 v[0:15], v[120:123], v[72:75], v[0:15]
	v_exp_f32_e32 v44, v44
	v_exp_f32_e32 v45, v45
	v_exp_f32_e32 v46, v46
	v_exp_f32_e32 v47, v47
	s_andn2_b64 vcc, exec, s[60:61]
	s_cbranch_vccnz .LBB0_587
	s_waitcnt lgkmcnt(0)
	v_add_u32_e32 v76, s54, v146
	ds_read_b128 v[64:67], v76 offset:96
	ds_read_b128 v[68:71], v76 offset:64
	ds_read_b128 v[72:75], v76 offset:32
	ds_read_b128 v[76:79], v76
	s_waitcnt lgkmcnt(3)
	v_pk_mul_f32 v[28:29], v[28:29], v[64:65]
	s_waitcnt lgkmcnt(2)
	v_pk_mul_f32 v[24:25], v[24:25], v[68:69]
	s_waitcnt lgkmcnt(1)
	v_pk_mul_f32 v[20:21], v[20:21], v[72:73]
	v_pk_mul_f32 v[30:31], v[30:31], v[66:67]
	v_pk_mul_f32 v[26:27], v[26:27], v[70:71]
	v_pk_mul_f32 v[22:23], v[22:23], v[74:75]
	s_waitcnt lgkmcnt(0)
	v_pk_mul_f32 v[18:19], v[18:19], v[78:79]
	v_pk_mul_f32 v[16:17], v[16:17], v[76:77]
	v_pk_mul_f32 v[12:13], v[12:13], v[64:65]
	v_pk_mul_f32 v[8:9], v[8:9], v[68:69]
	v_pk_mul_f32 v[4:5], v[4:5], v[72:73]
	v_pk_mul_f32 v[14:15], v[14:15], v[66:67]
	v_pk_mul_f32 v[10:11], v[10:11], v[70:71]
	v_pk_mul_f32 v[6:7], v[6:7], v[74:75]
	v_pk_mul_f32 v[2:3], v[2:3], v[78:79]
	v_pk_mul_f32 v[0:1], v[0:1], v[76:77]
